# speedup vs baseline: 1.0095x; 1.0018x over previous
.LBB0_354:
	v_mov_b32_e32 v134, v252
	s_movk_i32 s1, 0x1800
	v_and_b32_e32 v135, 15, v134
	v_ashrrev_i32_e32 v139, 2, v134
	v_lshlrev_b32_e32 v134, 3, v134
	v_and_b32_e32 v140, 24, v134
	v_and_b32_e32 v134, -4, v139
	v_lshl_add_u32 v143, v134, 2, s54
	ds_read_b128 v[144:147], v143
	v_lshl_add_u32 v138, v135, 2, s26
	v_mul_lo_u32 v135, v139, s94
	v_lshlrev_b32_e32 v141, 2, v140
	v_add3_u32 v141, s26, v135, v141
	v_add_u32_e32 v142, s16, v139
	v_mad_u64_u32 v[134:135], s[16:17], v134, s94, v[138:139]
	s_waitcnt lgkmcnt(0)
	v_mul_f32_e32 v122, v122, v144
	ds_write_b32 v134, v122
	v_mul_f32_e32 v122, v126, v144
	ds_write_b32 v134, v122 offset:64
	v_mul_f32_e32 v122, v123, v145
	ds_write_b32 v134, v122 offset:144
	v_mul_f32_e32 v122, v127, v145
	ds_write_b32 v134, v122 offset:208
	v_mul_f32_e32 v122, v124, v146
	ds_write_b32 v134, v122 offset:288
	v_mul_f32_e32 v122, v128, v146
	ds_write_b32 v134, v122 offset:352
	v_or_b32_e32 v122, 3, v139
	v_mad_u64_u32 v[122:123], s[16:17], v122, s94, v[138:139]
	v_mul_f32_e32 v123, v125, v147
	ds_write_b32 v122, v123
	v_mul_f32_e32 v123, v129, v147
	ds_write_b32 v122, v123 offset:64
	ds_read_b128 v[124:127], v141
	ds_read_b128 v[148:151], v141 offset:16
	v_mul_f32_e32 v114, v114, v144
	ds_write_b32 v134, v114
	v_mul_f32_e32 v114, v118, v144
	ds_write_b32 v134, v114 offset:64
	v_mul_f32_e32 v114, v115, v145
	v_add_u32_e32 v156, s46, v142
	s_waitcnt lgkmcnt(0)
	v_cvt_pk_bf16_f32 v152, v124, v125
	v_mov_b64_e32 v[124:125], s[6:7]
	ds_write_b32 v134, v114 offset:144
	v_mul_f32_e32 v114, v119, v145
	v_cvt_pk_bf16_f32 v153, v126, v127
	v_mad_i64_i32 v[126:127], s[16:17], v156, s1, v[124:125]
	s_lshl_b64 s[12:13], s[12:13], 1
	ds_write_b32 v134, v114 offset:208
	v_mul_f32_e32 v114, v116, v146
	v_lshl_add_u64 v[126:127], v[126:127], 0, s[12:13]
	ds_write_b32 v134, v114 offset:288
	v_mul_f32_e32 v114, v120, v146
	v_lshl_add_u64 v[128:129], v[126:127], 0, s[74:75]
	v_lshlrev_b32_e32 v126, 1, v140
	v_mov_b32_e32 v127, v0
	ds_write_b32 v134, v114 offset:352
	v_mul_f32_e32 v114, v117, v147
	v_lshl_add_u64 v[128:129], v[128:129], 0, v[126:127]
	ds_write_b32 v122, v114
	v_mul_f32_e32 v114, v121, v147
	v_cvt_pk_bf16_f32 v154, v148, v149
	v_cvt_pk_bf16_f32 v155, v150, v151
	global_store_dwordx4 v[128:129], v[152:155], off
	ds_write_b32 v122, v114 offset:64
	ds_read_b128 v[114:117], v141
	ds_read_b128 v[118:121], v141 offset:16
	s_waitcnt lgkmcnt(0)
	v_cvt_pk_bf16_f32 v114, v114, v115
	v_cvt_pk_bf16_f32 v115, v116, v117
	v_cvt_pk_bf16_f32 v116, v118, v119
	v_cvt_pk_bf16_f32 v117, v120, v121
	global_store_dwordx4 v[128:129], v[114:117], off offset:256
	ds_read_b128 v[114:117], v143 offset:64
	v_add_u32_e32 v118, s47, v142
	s_and_b64 vcc, exec, s[14:15]
	s_waitcnt lgkmcnt(0)
	v_mul_f32_e32 v106, v106, v114
	ds_write_b32 v134, v106
	v_mul_f32_e32 v106, v110, v114
	ds_write_b32 v134, v106 offset:64
	v_mul_f32_e32 v106, v107, v115
	ds_write_b32 v134, v106 offset:144
	v_mul_f32_e32 v106, v111, v115
	ds_write_b32 v134, v106 offset:208
	v_mul_f32_e32 v106, v108, v116
	ds_write_b32 v134, v106 offset:288
	v_mul_f32_e32 v106, v112, v116
	ds_write_b32 v134, v106 offset:352
	v_mul_f32_e32 v106, v109, v117
	ds_write_b32 v122, v106
	v_mul_f32_e32 v106, v113, v117
	ds_write_b32 v122, v106 offset:64
	ds_read_b128 v[106:109], v141
	ds_read_b128 v[110:113], v141 offset:16
	v_mul_f32_e32 v98, v98, v114
	ds_write_b32 v134, v98
	v_mul_f32_e32 v98, v102, v114
	ds_write_b32 v134, v98 offset:64
	v_mul_f32_e32 v98, v99, v115
	ds_write_b32 v134, v98 offset:144
	v_mul_f32_e32 v98, v103, v115
	s_waitcnt lgkmcnt(0)
	v_cvt_pk_bf16_f32 v106, v106, v107
	v_cvt_pk_bf16_f32 v107, v108, v109
	v_cvt_pk_bf16_f32 v108, v110, v111
	v_mad_i64_i32 v[110:111], s[16:17], v118, s1, v[124:125]
	ds_write_b32 v134, v98 offset:208
	v_mul_f32_e32 v98, v100, v116
	v_lshl_add_u64 v[110:111], v[110:111], 0, s[12:13]
	ds_write_b32 v134, v98 offset:288
	v_mul_f32_e32 v98, v104, v116
	v_lshl_add_u64 v[110:111], v[110:111], 0, s[74:75]
	ds_write_b32 v134, v98 offset:352
	v_mul_f32_e32 v98, v101, v117
	v_lshl_add_u64 v[110:111], v[110:111], 0, v[126:127]
	ds_write_b32 v122, v98
	v_mul_f32_e32 v98, v105, v117
	v_cvt_pk_bf16_f32 v109, v112, v113
	global_store_dwordx4 v[110:111], v[106:109], off
	ds_write_b32 v122, v98 offset:64
	ds_read_b128 v[98:101], v141
	ds_read_b128 v[102:105], v141 offset:16
	s_waitcnt lgkmcnt(0)
	v_cvt_pk_bf16_f32 v98, v98, v99
	v_cvt_pk_bf16_f32 v99, v100, v101
	v_cvt_pk_bf16_f32 v100, v102, v103
	v_cvt_pk_bf16_f32 v101, v104, v105
	global_store_dwordx4 v[110:111], v[98:101], off offset:256
	ds_read_b128 v[98:101], v143 offset:128
	v_add_u32_e32 v102, s48, v142
	s_waitcnt lgkmcnt(0)
	v_mul_f32_e32 v90, v90, v98
	ds_write_b32 v134, v90
	v_mul_f32_e32 v90, v94, v98
	ds_write_b32 v134, v90 offset:64
	v_mul_f32_e32 v90, v91, v99
	ds_write_b32 v134, v90 offset:144
	v_mul_f32_e32 v90, v95, v99
	ds_write_b32 v134, v90 offset:208
	v_mul_f32_e32 v90, v92, v100
	ds_write_b32 v134, v90 offset:288
	v_mul_f32_e32 v90, v96, v100
	ds_write_b32 v134, v90 offset:352
	v_mul_f32_e32 v90, v93, v101
	ds_write_b32 v122, v90
	v_mul_f32_e32 v90, v97, v101
	ds_write_b32 v122, v90 offset:64
	ds_read_b128 v[90:93], v141
	ds_read_b128 v[94:97], v141 offset:16
	v_mul_f32_e32 v82, v82, v98
	ds_write_b32 v134, v82
	v_mul_f32_e32 v82, v86, v98
	ds_write_b32 v134, v82 offset:64
	v_mul_f32_e32 v82, v83, v99
	ds_write_b32 v134, v82 offset:144
	v_mul_f32_e32 v82, v87, v99
	s_waitcnt lgkmcnt(0)
	v_cvt_pk_bf16_f32 v90, v90, v91
	v_cvt_pk_bf16_f32 v91, v92, v93
	v_cvt_pk_bf16_f32 v92, v94, v95
	v_mad_i64_i32 v[94:95], s[16:17], v102, s1, v[124:125]
	ds_write_b32 v134, v82 offset:208
	v_mul_f32_e32 v82, v84, v100
	v_lshl_add_u64 v[94:95], v[94:95], 0, s[12:13]
	ds_write_b32 v134, v82 offset:288
	v_mul_f32_e32 v82, v88, v100
	v_lshl_add_u64 v[94:95], v[94:95], 0, s[74:75]
	ds_write_b32 v134, v82 offset:352
	v_mul_f32_e32 v82, v85, v101
	v_lshl_add_u64 v[94:95], v[94:95], 0, v[126:127]
	ds_write_b32 v122, v82
	v_mul_f32_e32 v82, v89, v101
	v_cvt_pk_bf16_f32 v93, v96, v97
	global_store_dwordx4 v[94:95], v[90:93], off
	ds_write_b32 v122, v82 offset:64
	ds_read_b128 v[82:85], v141
	ds_read_b128 v[86:89], v141 offset:16
	s_waitcnt lgkmcnt(0)
	v_cvt_pk_bf16_f32 v82, v82, v83
	v_cvt_pk_bf16_f32 v83, v84, v85
	v_cvt_pk_bf16_f32 v84, v86, v87
	v_cvt_pk_bf16_f32 v85, v88, v89
	global_store_dwordx4 v[94:95], v[82:85], off offset:256
	ds_read_b128 v[82:85], v143 offset:192
	v_add_u32_e32 v86, s49, v142
	s_waitcnt lgkmcnt(0)
	v_mul_f32_e32 v74, v74, v82
	ds_write_b32 v134, v74
	v_mul_f32_e32 v74, v78, v82
	ds_write_b32 v134, v74 offset:64
	v_mul_f32_e32 v74, v75, v83
	ds_write_b32 v134, v74 offset:144
	v_mul_f32_e32 v74, v79, v83
	ds_write_b32 v134, v74 offset:208
	v_mul_f32_e32 v74, v76, v84
	ds_write_b32 v134, v74 offset:288
	v_mul_f32_e32 v74, v80, v84
	ds_write_b32 v134, v74 offset:352
	v_mul_f32_e32 v74, v77, v85
	ds_write_b32 v122, v74
	v_mul_f32_e32 v74, v81, v85
	ds_write_b32 v122, v74 offset:64
	ds_read_b128 v[74:77], v141
	ds_read_b128 v[78:81], v141 offset:16
	v_mul_f32_e32 v66, v66, v82
	ds_write_b32 v134, v66
	v_mul_f32_e32 v66, v70, v82
	ds_write_b32 v134, v66 offset:64
	v_mul_f32_e32 v66, v67, v83
	ds_write_b32 v134, v66 offset:144
	v_mul_f32_e32 v66, v71, v83
	s_waitcnt lgkmcnt(0)
	v_cvt_pk_bf16_f32 v74, v74, v75
	v_cvt_pk_bf16_f32 v75, v76, v77
	v_cvt_pk_bf16_f32 v76, v78, v79
	v_mad_i64_i32 v[78:79], s[16:17], v86, s1, v[124:125]
	ds_write_b32 v134, v66 offset:208
	v_mul_f32_e32 v66, v68, v84
	v_lshl_add_u64 v[78:79], v[78:79], 0, s[12:13]
	ds_write_b32 v134, v66 offset:288
	v_mul_f32_e32 v66, v72, v84
	v_lshl_add_u64 v[78:79], v[78:79], 0, s[74:75]
	ds_write_b32 v134, v66 offset:352
	v_mul_f32_e32 v66, v69, v85
	v_lshl_add_u64 v[78:79], v[78:79], 0, v[126:127]
	ds_write_b32 v122, v66
	v_mul_f32_e32 v66, v73, v85
	v_cvt_pk_bf16_f32 v77, v80, v81
	global_store_dwordx4 v[78:79], v[74:77], off
	ds_write_b32 v122, v66 offset:64
	ds_read_b128 v[66:69], v141
	ds_read_b128 v[70:73], v141 offset:16
	s_waitcnt lgkmcnt(0)
	v_cvt_pk_bf16_f32 v66, v66, v67
	v_cvt_pk_bf16_f32 v67, v68, v69
	v_cvt_pk_bf16_f32 v68, v70, v71
	v_cvt_pk_bf16_f32 v69, v72, v73
	global_store_dwordx4 v[78:79], v[66:69], off offset:256
	ds_read_b128 v[66:69], v143 offset:512
	v_add_u32_e32 v70, s50, v142
	s_waitcnt lgkmcnt(0)
	v_mul_f32_e32 v58, v58, v66
	ds_write_b32 v134, v58
	v_mul_f32_e32 v58, v62, v66
	ds_write_b32 v134, v58 offset:64
	v_mul_f32_e32 v58, v59, v67
	ds_write_b32 v134, v58 offset:144
	v_mul_f32_e32 v58, v63, v67
	ds_write_b32 v134, v58 offset:208
	v_mul_f32_e32 v58, v60, v68
	ds_write_b32 v134, v58 offset:288
	v_mul_f32_e32 v58, v64, v68
	ds_write_b32 v134, v58 offset:352
	v_mul_f32_e32 v58, v61, v69
	ds_write_b32 v122, v58
	v_mul_f32_e32 v58, v65, v69
	ds_write_b32 v122, v58 offset:64
	ds_read_b128 v[58:61], v141
	ds_read_b128 v[62:65], v141 offset:16
	v_mul_f32_e32 v50, v50, v66
	ds_write_b32 v134, v50
	v_mul_f32_e32 v50, v54, v66
	ds_write_b32 v134, v50 offset:64
	v_mul_f32_e32 v50, v51, v67
	ds_write_b32 v134, v50 offset:144
	v_mul_f32_e32 v50, v55, v67
	s_waitcnt lgkmcnt(0)
	v_cvt_pk_bf16_f32 v58, v58, v59
	v_cvt_pk_bf16_f32 v59, v60, v61
	v_cvt_pk_bf16_f32 v60, v62, v63
	v_mad_i64_i32 v[62:63], s[16:17], v70, s1, v[124:125]
	ds_write_b32 v134, v50 offset:208
	v_mul_f32_e32 v50, v52, v68
	v_lshl_add_u64 v[62:63], v[62:63], 0, s[12:13]
	ds_write_b32 v134, v50 offset:288
	v_mul_f32_e32 v50, v56, v68
	v_lshl_add_u64 v[62:63], v[62:63], 0, s[74:75]
	ds_write_b32 v134, v50 offset:352
	v_mul_f32_e32 v50, v53, v69
	v_lshl_add_u64 v[62:63], v[62:63], 0, v[126:127]
	ds_write_b32 v122, v50
	v_mul_f32_e32 v50, v57, v69
	v_cvt_pk_bf16_f32 v61, v64, v65
	global_store_dwordx4 v[62:63], v[58:61], off
	ds_write_b32 v122, v50 offset:64
	ds_read_b128 v[50:53], v141
	ds_read_b128 v[54:57], v141 offset:16
	s_waitcnt lgkmcnt(0)
	v_cvt_pk_bf16_f32 v50, v50, v51
	v_cvt_pk_bf16_f32 v51, v52, v53
	v_cvt_pk_bf16_f32 v52, v54, v55
	v_cvt_pk_bf16_f32 v53, v56, v57
	global_store_dwordx4 v[62:63], v[50:53], off offset:256
	ds_read_b128 v[50:53], v143 offset:576
	v_add_u32_e32 v54, s51, v142
	s_waitcnt lgkmcnt(0)
	v_mul_f32_e32 v42, v42, v50
	ds_write_b32 v134, v42
	v_mul_f32_e32 v42, v46, v50
	ds_write_b32 v134, v42 offset:64
	v_mul_f32_e32 v42, v43, v51
	ds_write_b32 v134, v42 offset:144
	v_mul_f32_e32 v42, v47, v51
	ds_write_b32 v134, v42 offset:208
	v_mul_f32_e32 v42, v44, v52
	ds_write_b32 v134, v42 offset:288
	v_mul_f32_e32 v42, v48, v52
	ds_write_b32 v134, v42 offset:352
	v_mul_f32_e32 v42, v45, v53
	ds_write_b32 v122, v42
	v_mul_f32_e32 v42, v49, v53
	ds_write_b32 v122, v42 offset:64
	ds_read_b128 v[42:45], v141
	ds_read_b128 v[46:49], v141 offset:16
	v_mul_f32_e32 v34, v34, v50
	ds_write_b32 v134, v34
	v_mul_f32_e32 v34, v38, v50
	ds_write_b32 v134, v34 offset:64
	v_mul_f32_e32 v34, v35, v51
	ds_write_b32 v134, v34 offset:144
	v_mul_f32_e32 v34, v39, v51
	s_waitcnt lgkmcnt(0)
	v_cvt_pk_bf16_f32 v42, v42, v43
	v_cvt_pk_bf16_f32 v43, v44, v45
	v_cvt_pk_bf16_f32 v44, v46, v47
	v_mad_i64_i32 v[46:47], s[16:17], v54, s1, v[124:125]
	ds_write_b32 v134, v34 offset:208
	v_mul_f32_e32 v34, v36, v52
	v_lshl_add_u64 v[46:47], v[46:47], 0, s[12:13]
	ds_write_b32 v134, v34 offset:288
	v_mul_f32_e32 v34, v40, v52
	v_lshl_add_u64 v[46:47], v[46:47], 0, s[74:75]
	ds_write_b32 v134, v34 offset:352
	v_mul_f32_e32 v34, v37, v53
	v_lshl_add_u64 v[46:47], v[46:47], 0, v[126:127]
	ds_write_b32 v122, v34
	v_mul_f32_e32 v34, v41, v53
	v_cvt_pk_bf16_f32 v45, v48, v49
	global_store_dwordx4 v[46:47], v[42:45], off
	ds_write_b32 v122, v34 offset:64
	ds_read_b128 v[34:37], v141
	ds_read_b128 v[38:41], v141 offset:16
	s_waitcnt lgkmcnt(0)
	v_cvt_pk_bf16_f32 v34, v34, v35
	v_cvt_pk_bf16_f32 v35, v36, v37
	v_cvt_pk_bf16_f32 v36, v38, v39
	v_cvt_pk_bf16_f32 v37, v40, v41
	global_store_dwordx4 v[46:47], v[34:37], off offset:256
	ds_read_b128 v[34:37], v143 offset:640
	v_add_u32_e32 v38, s52, v142
	s_waitcnt lgkmcnt(0)
	v_mul_f32_e32 v26, v26, v34
	ds_write_b32 v134, v26
	v_mul_f32_e32 v26, v30, v34
	ds_write_b32 v134, v26 offset:64
	v_mul_f32_e32 v26, v27, v35
	ds_write_b32 v134, v26 offset:144
	v_mul_f32_e32 v26, v31, v35
	ds_write_b32 v134, v26 offset:208
	v_mul_f32_e32 v26, v28, v36
	ds_write_b32 v134, v26 offset:288
	v_mul_f32_e32 v26, v32, v36
	ds_write_b32 v134, v26 offset:352
	v_mul_f32_e32 v26, v29, v37
	ds_write_b32 v122, v26
	v_mul_f32_e32 v26, v33, v37
	ds_write_b32 v122, v26 offset:64
	ds_read_b128 v[26:29], v141
	ds_read_b128 v[30:33], v141 offset:16
	v_mul_f32_e32 v18, v18, v34
	ds_write_b32 v134, v18
	v_mul_f32_e32 v18, v22, v34
	ds_write_b32 v134, v18 offset:64
	v_mul_f32_e32 v18, v19, v35
	ds_write_b32 v134, v18 offset:144
	v_mul_f32_e32 v18, v23, v35
	s_waitcnt lgkmcnt(0)
	v_cvt_pk_bf16_f32 v26, v26, v27
	v_cvt_pk_bf16_f32 v27, v28, v29
	v_cvt_pk_bf16_f32 v28, v30, v31
	v_mad_i64_i32 v[30:31], s[16:17], v38, s1, v[124:125]
	ds_write_b32 v134, v18 offset:208
	v_mul_f32_e32 v18, v20, v36
	v_lshl_add_u64 v[30:31], v[30:31], 0, s[12:13]
	ds_write_b32 v134, v18 offset:288
	v_mul_f32_e32 v18, v24, v36
	v_lshl_add_u64 v[30:31], v[30:31], 0, s[74:75]
	ds_write_b32 v134, v18 offset:352
	v_mul_f32_e32 v18, v21, v37
	v_lshl_add_u64 v[30:31], v[30:31], 0, v[126:127]
	ds_write_b32 v122, v18
	v_mul_f32_e32 v18, v25, v37
	v_cvt_pk_bf16_f32 v29, v32, v33
	global_store_dwordx4 v[30:31], v[26:29], off
	ds_write_b32 v122, v18 offset:64
	ds_read_b128 v[18:21], v141
	ds_read_b128 v[22:25], v141 offset:16
	s_waitcnt lgkmcnt(0)
	v_cvt_pk_bf16_f32 v18, v18, v19
	v_cvt_pk_bf16_f32 v19, v20, v21
	v_cvt_pk_bf16_f32 v20, v22, v23
	v_cvt_pk_bf16_f32 v21, v24, v25
	global_store_dwordx4 v[30:31], v[18:21], off offset:256
	ds_read_b128 v[18:21], v143 offset:704
	v_add_u32_e32 v22, s53, v142
	s_waitcnt lgkmcnt(0)
	v_mul_f32_e32 v10, v10, v18
	ds_write_b32 v134, v10
	v_mul_f32_e32 v10, v14, v18
	ds_write_b32 v134, v10 offset:64
	v_mul_f32_e32 v10, v11, v19
	ds_write_b32 v134, v10 offset:144
	v_mul_f32_e32 v10, v15, v19
	ds_write_b32 v134, v10 offset:208
	v_mul_f32_e32 v10, v12, v20
	ds_write_b32 v134, v10 offset:288
	v_mul_f32_e32 v10, v16, v20
	ds_write_b32 v134, v10 offset:352
	v_mul_f32_e32 v10, v13, v21
	ds_write_b32 v122, v10
	v_mul_f32_e32 v10, v17, v21
	ds_write_b32 v122, v10 offset:64
	ds_read_b128 v[10:13], v141
	ds_read_b128 v[14:17], v141 offset:16
	v_mul_f32_e32 v2, v2, v18
	ds_write_b32 v134, v2
	v_mul_f32_e32 v2, v6, v18
	ds_write_b32 v134, v2 offset:64
	v_mul_f32_e32 v2, v3, v19
	ds_write_b32 v134, v2 offset:144
	v_mul_f32_e32 v2, v7, v19
	s_waitcnt lgkmcnt(0)
	v_cvt_pk_bf16_f32 v10, v10, v11
	v_cvt_pk_bf16_f32 v11, v12, v13
	v_cvt_pk_bf16_f32 v12, v14, v15
	v_mad_i64_i32 v[14:15], s[16:17], v22, s1, v[124:125]
	ds_write_b32 v134, v2 offset:208
	v_mul_f32_e32 v2, v4, v20
	v_lshl_add_u64 v[14:15], v[14:15], 0, s[12:13]
	ds_write_b32 v134, v2 offset:288
	v_mul_f32_e32 v2, v8, v20
	v_lshl_add_u64 v[14:15], v[14:15], 0, s[74:75]
	ds_write_b32 v134, v2 offset:352
	v_mul_f32_e32 v2, v5, v21
	v_lshl_add_u64 v[14:15], v[14:15], 0, v[126:127]
	ds_write_b32 v122, v2
	v_mul_f32_e32 v2, v9, v21
	v_cvt_pk_bf16_f32 v13, v16, v17
	global_store_dwordx4 v[14:15], v[10:13], off
	ds_write_b32 v122, v2 offset:64
	ds_read_b128 v[2:5], v141
	ds_read_b128 v[6:9], v141 offset:16
	s_waitcnt lgkmcnt(0)
	v_cvt_pk_bf16_f32 v2, v2, v3
	v_cvt_pk_bf16_f32 v3, v4, v5
	v_cvt_pk_bf16_f32 v4, v6, v7
	v_cvt_pk_bf16_f32 v5, v8, v9
	global_store_dwordx4 v[14:15], v[2:5], off offset:256
	s_waitcnt vmcnt(32)
	v_add_f32_e32 v164, v160, v161
	v_add_f32_e32 v164, v162, v164
	v_add_f32_e32 v164, v163, v164
	v_fmamk_f32 v164, v164, 0x3a800000, v208
	v_mul_f32_e32 v165, 0x4b800000, v164
	v_cmp_gt_f32_e64 s[12:13], s95, v164
	s_nop 1
	v_cndmask_b32_e64 v164, v164, v165, s[12:13]
	v_rsq_f32_e32 v164, v164
	s_nop 0
	v_mul_f32_e32 v165, 0x45800000, v164
	v_cndmask_b32_e64 v206, v164, v165, s[12:13]
	s_barrier
	s_cbranch_vccnz .LBB0_370

.LBB0_367:
	s_add_i32 s55, s55, s73
	s_cmpk_gt_i32 s55, 0x5ff
	s_cselect_b64 s[14:15], -1, 0
	s_and_b64 vcc, exec, s[14:15]
	s_cbranch_vccnz .LBB0_354
	s_mul_hi_i32 s17, s55, 0x2aaaaaab
	s_lshr_b32 s18, s17, 31
	s_ashr_i32 s17, s17, 4
	s_add_i32 s17, s17, s18
	s_lshl_b32 s19, s55, 8
	s_lshl_b32 s18, s17, 11
	s_and_b32 s19, s19, 0x700
	s_or_b32 s18, s18, s19
	s_and_saveexec_b64 s[20:21], s[4:5]
	s_cbranch_execz .LBB0_353
	v_add_u32_e32 v134, s18, v1
	v_ashrrev_i32_e32 v135, 31, v134
	v_lshl_add_u64 v[134:135], v[134:135], 4, s[2:3]
	global_load_dwordx4 v[160:163], v[134:135], off
	s_branch .LBB0_353

.LBB0_458:
	v_mov_b32_e32 v134, v253
	s_movk_i32 s18, 0x1600
	v_and_b32_e32 v135, 15, v134
	v_ashrrev_i32_e32 v139, 2, v134
	v_lshlrev_b32_e32 v134, 3, v134
	v_and_b32_e32 v140, 24, v134
	v_and_b32_e32 v134, -4, v139
	v_lshl_add_u32 v142, v134, 2, s48
	ds_read_b128 v[144:147], v142
	v_lshl_add_u32 v138, v135, 2, s24
	v_mul_lo_u32 v135, v139, s94
	v_lshlrev_b32_e32 v141, 2, v140
	v_add3_u32 v141, s24, v135, v141
	s_waitcnt lgkmcnt(0)
	v_mul_f32_e32 v143, 0xbfb8aa3b, v144
	v_mul_f32_e32 v135, v118, v143
	v_exp_f32_e32 v152, v135
	v_mad_u64_u32 v[134:135], s[16:17], v134, s94, v[138:139]
	v_mul_f32_e32 v118, v118, v126
	v_add_f32_e32 v135, 1.0, v152
	v_rcp_f32_e32 v135, v135
	v_mul_f32_e32 v126, v114, v143
	v_exp_f32_e32 v126, v126
	v_pk_mul_f32 v[150:151], v[144:145], v[144:145]
	v_mul_f32_e32 v114, v114, v122
	v_mul_f32_e32 v135, v150, v135
	v_mul_f32_e32 v118, v118, v135
	ds_write_b32 v134, v118
	v_add_f32_e32 v118, 1.0, v126
	v_rcp_f32_e32 v118, v118
	v_mul_f32_e32 v122, 0xbfb8aa3b, v145
	v_mul_f32_e32 v126, v119, v122
	v_exp_f32_e32 v126, v126
	v_mul_f32_e32 v118, v150, v118
	v_mul_f32_e32 v114, v114, v118
	ds_write_b32 v134, v114 offset:64
	v_add_f32_e32 v114, 1.0, v126
	v_rcp_f32_e32 v114, v114
	v_mul_f32_e32 v118, v119, v127
	v_mul_f32_e32 v119, v115, v122
	v_exp_f32_e32 v119, v119
	v_mul_f32_e32 v114, v151, v114
	v_mul_f32_e32 v114, v118, v114
	ds_write_b32 v134, v114 offset:144
	v_add_f32_e32 v114, 1.0, v119
	v_mul_f32_e32 v118, 0xbfb8aa3b, v146
	v_rcp_f32_e32 v114, v114
	v_mul_f32_e32 v119, v120, v118
	v_exp_f32_e32 v119, v119
	v_mul_f32_e32 v118, v116, v118
	v_mul_f32_e32 v115, v115, v123
	v_mul_f32_e32 v114, v151, v114
	v_exp_f32_e32 v118, v118
	v_mul_f32_e32 v114, v115, v114
	v_add_f32_e32 v115, 1.0, v119
	v_rcp_f32_e32 v115, v115
	v_add_f32_e32 v118, 1.0, v118
	v_pk_mul_f32 v[148:149], v[146:147], v[146:147]
	v_rcp_f32_e32 v118, v118
	ds_write_b32 v134, v114 offset:208
	v_mul_f32_e32 v114, v120, v128
	v_mul_f32_e32 v115, v148, v115
	v_mul_f32_e32 v114, v114, v115
	ds_write_b32 v134, v114 offset:288
	v_mul_f32_e32 v114, v116, v124
	v_mul_f32_e32 v116, 0xbfb8aa3b, v147
	v_mul_f32_e32 v115, v148, v118
	v_mul_f32_e32 v118, v121, v116
	v_exp_f32_e32 v118, v118
	v_mul_f32_e32 v114, v114, v115
	ds_write_b32 v134, v114 offset:352
	v_or_b32_e32 v114, 3, v139
	v_add_f32_e32 v115, 1.0, v118
	v_rcp_f32_e32 v118, v115
	v_mul_f32_e32 v115, v117, v116
	v_exp_f32_e32 v116, v115
	v_mad_u64_u32 v[114:115], s[16:17], v114, s94, v[138:139]
	v_mul_f32_e32 v115, v121, v129
	v_add_f32_e32 v116, 1.0, v116
	v_rcp_f32_e32 v116, v116
	v_mul_f32_e32 v118, v149, v118
	v_mul_f32_e32 v115, v115, v118
	ds_write_b32 v114, v115
	v_mul_f32_e32 v115, v117, v125
	v_mul_f32_e32 v116, v149, v116
	v_mul_f32_e32 v115, v115, v116
	ds_write_b32 v114, v115 offset:64
	ds_read_b128 v[116:119], v141
	ds_read_b128 v[120:123], v141 offset:16
	s_waitcnt lgkmcnt(0)
	v_cvt_pk_bf16_f32 v126, v120, v121
	v_cvt_pk_bf16_f32 v127, v122, v123
	ds_read_b128 v[120:123], v142 offset:64
	v_add_u32_e32 v135, s12, v139
	s_lshl_b32 s12, s50, 7
	s_ashr_i32 s13, s12, 31
	v_cvt_pk_bf16_f32 v124, v116, v117
	v_add_u32_e32 v115, s44, v135
	v_mov_b64_e32 v[116:117], s[6:7]
	v_cvt_pk_bf16_f32 v125, v118, v119
	v_mad_i64_i32 v[118:119], s[16:17], v115, s18, v[116:117]
	s_lshl_b64 s[12:13], s[12:13], 1
	v_lshl_add_u64 v[118:119], v[118:119], 0, s[12:13]
	v_lshl_add_u64 v[128:129], v[118:119], 0, s[74:75]
	s_waitcnt lgkmcnt(0)
	v_mul_f32_e32 v119, 0xbfb8aa3b, v120
	v_mul_f32_e32 v118, v102, v119
	v_exp_f32_e32 v143, v118
	v_pk_mul_f32 v[144:145], v[120:121], v[120:121]
	v_mul_f32_e32 v102, v102, v110
	v_mul_f32_e32 v110, v98, v119
	v_add_f32_e32 v120, 1.0, v143
	v_rcp_f32_e32 v120, v120
	v_exp_f32_e32 v110, v110
	v_mul_f32_e32 v98, v98, v106
	v_mul_f32_e32 v106, 0xbfb8aa3b, v121
	v_mul_f32_e32 v119, v144, v120
	v_mul_f32_e32 v102, v102, v119
	ds_write_b32 v134, v102
	v_add_f32_e32 v102, 1.0, v110
	v_rcp_f32_e32 v102, v102
	v_mul_f32_e32 v110, v103, v106
	v_exp_f32_e32 v110, v110
	v_pk_mul_f32 v[138:139], v[122:123], v[122:123]
	v_mul_f32_e32 v102, v144, v102
	v_mul_f32_e32 v98, v98, v102
	ds_write_b32 v134, v98 offset:64
	v_add_f32_e32 v98, 1.0, v110
	v_rcp_f32_e32 v98, v98
	v_mul_f32_e32 v102, v103, v111
	v_mul_f32_e32 v103, v99, v106
	v_exp_f32_e32 v103, v103
	v_mul_f32_e32 v98, v145, v98
	v_mul_f32_e32 v98, v102, v98
	ds_write_b32 v134, v98 offset:144
	v_add_f32_e32 v98, 1.0, v103
	v_rcp_f32_e32 v98, v98
	v_mul_f32_e32 v102, 0xbfb8aa3b, v122
	v_mul_f32_e32 v103, v104, v102
	v_exp_f32_e32 v103, v103
	v_mul_f32_e32 v99, v99, v107
	v_mul_f32_e32 v98, v145, v98
	v_mul_f32_e32 v98, v99, v98
	ds_write_b32 v134, v98 offset:208
	v_add_f32_e32 v98, 1.0, v103
	v_rcp_f32_e32 v98, v98
	v_mul_f32_e32 v102, v100, v102
	v_exp_f32_e32 v102, v102
	v_mul_f32_e32 v99, v104, v112
	v_mul_f32_e32 v98, v138, v98
	v_mul_f32_e32 v98, v99, v98
	ds_write_b32 v134, v98 offset:288
	v_add_f32_e32 v98, 1.0, v102
	v_mul_f32_e32 v99, 0xbfb8aa3b, v123
	v_rcp_f32_e32 v98, v98
	v_mul_f32_e32 v102, v105, v99
	v_exp_f32_e32 v102, v102
	v_mul_f32_e32 v99, v101, v99
	v_exp_f32_e32 v99, v99
	v_mul_f32_e32 v100, v100, v108
	v_mul_f32_e32 v98, v138, v98
	v_mul_f32_e32 v98, v100, v98
	v_add_f32_e32 v100, 1.0, v102
	v_rcp_f32_e32 v100, v100
	v_add_f32_e32 v99, 1.0, v99
	v_rcp_f32_e32 v99, v99
	ds_write_b32 v134, v98 offset:352
	v_mul_f32_e32 v98, v105, v113
	v_mul_f32_e32 v100, v139, v100
	v_mul_f32_e32 v98, v98, v100
	ds_write_b32 v114, v98
	v_mul_f32_e32 v98, v101, v109
	v_mul_f32_e32 v99, v139, v99
	v_lshlrev_b32_e32 v118, 1, v140
	v_mul_f32_e32 v98, v98, v99
	v_mov_b32_e32 v119, v0
	ds_write_b32 v114, v98 offset:64
	v_lshl_add_u64 v[106:107], v[128:129], 0, v[118:119]
	global_store_dwordx4 v[106:107], v[124:127], off
	ds_read_b128 v[106:109], v142 offset:128
	ds_read_b128 v[98:101], v141
	ds_read_b128 v[102:105], v141 offset:16
	s_waitcnt lgkmcnt(0)
	v_cvt_pk_bf16_f32 v98, v98, v99
	v_cvt_pk_bf16_f32 v99, v100, v101
	v_mul_f32_e32 v112, 0xbfb8aa3b, v106
	v_cvt_pk_bf16_f32 v101, v104, v105
	v_mul_f32_e32 v104, v86, v112
	v_exp_f32_e32 v113, v104
	v_pk_mul_f32 v[110:111], v[106:107], v[106:107]
	v_mul_f32_e32 v86, v86, v94
	v_mul_f32_e32 v94, v82, v112
	v_add_f32_e32 v106, 1.0, v113
	v_rcp_f32_e32 v106, v106
	v_exp_f32_e32 v94, v94
	v_mul_f32_e32 v82, v82, v90
	v_mul_f32_e32 v90, 0xbfb8aa3b, v107
	v_mul_f32_e32 v106, v110, v106
	v_mul_f32_e32 v86, v86, v106
	ds_write_b32 v134, v86
	v_add_f32_e32 v86, 1.0, v94
	v_rcp_f32_e32 v86, v86
	v_mul_f32_e32 v94, v87, v90
	v_exp_f32_e32 v94, v94
	v_pk_mul_f32 v[104:105], v[108:109], v[108:109]
	v_mul_f32_e32 v86, v110, v86
	v_mul_f32_e32 v82, v82, v86
	ds_write_b32 v134, v82 offset:64
	v_add_f32_e32 v82, 1.0, v94
	v_rcp_f32_e32 v82, v82
	v_mul_f32_e32 v86, v87, v95
	v_mul_f32_e32 v87, v83, v90
	v_exp_f32_e32 v87, v87
	v_mul_f32_e32 v82, v111, v82
	v_mul_f32_e32 v82, v86, v82
	ds_write_b32 v134, v82 offset:144
	v_add_f32_e32 v82, 1.0, v87
	v_rcp_f32_e32 v82, v82
	v_mul_f32_e32 v86, 0xbfb8aa3b, v108
	v_mul_f32_e32 v87, v88, v86
	v_exp_f32_e32 v87, v87
	v_mul_f32_e32 v83, v83, v91
	v_mul_f32_e32 v82, v111, v82
	v_mul_f32_e32 v82, v83, v82
	ds_write_b32 v134, v82 offset:208
	v_add_f32_e32 v82, 1.0, v87
	v_rcp_f32_e32 v82, v82
	v_mul_f32_e32 v86, v84, v86
	v_exp_f32_e32 v86, v86
	v_mul_f32_e32 v83, v88, v96
	v_mul_f32_e32 v82, v104, v82
	v_mul_f32_e32 v82, v83, v82
	ds_write_b32 v134, v82 offset:288
	v_add_f32_e32 v82, 1.0, v86
	v_mul_f32_e32 v83, 0xbfb8aa3b, v109
	v_rcp_f32_e32 v82, v82
	v_mul_f32_e32 v86, v89, v83
	v_exp_f32_e32 v86, v86
	v_mul_f32_e32 v83, v85, v83
	v_exp_f32_e32 v83, v83
	v_mul_f32_e32 v84, v84, v92
	v_mul_f32_e32 v82, v104, v82
	v_mul_f32_e32 v82, v84, v82
	v_add_f32_e32 v84, 1.0, v86
	v_rcp_f32_e32 v84, v84
	v_add_f32_e32 v83, 1.0, v83
	v_rcp_f32_e32 v83, v83
	v_cvt_pk_bf16_f32 v100, v102, v103
	v_add_u32_e32 v102, s45, v135
	ds_write_b32 v134, v82 offset:352
	v_mul_f32_e32 v82, v89, v97
	v_mul_f32_e32 v84, v105, v84
	v_mad_i64_i32 v[102:103], s[16:17], v102, s18, v[116:117]
	v_mul_f32_e32 v82, v82, v84
	v_lshl_add_u64 v[102:103], v[102:103], 0, s[12:13]
	ds_write_b32 v114, v82
	v_mul_f32_e32 v82, v85, v93
	v_mul_f32_e32 v83, v105, v83
	v_mul_f32_e32 v82, v82, v83
	v_lshl_add_u64 v[90:91], v[102:103], 0, s[74:75]
	ds_write_b32 v114, v82 offset:64
	v_lshl_add_u64 v[90:91], v[90:91], 0, v[118:119]
	global_store_dwordx4 v[90:91], v[98:101], off
	ds_read_b128 v[90:93], v142 offset:192
	ds_read_b128 v[82:85], v141
	ds_read_b128 v[86:89], v141 offset:16
	s_waitcnt lgkmcnt(0)
	v_cvt_pk_bf16_f32 v82, v82, v83
	v_cvt_pk_bf16_f32 v83, v84, v85
	v_mul_f32_e32 v96, 0xbfb8aa3b, v90
	v_cvt_pk_bf16_f32 v85, v88, v89
	v_mul_f32_e32 v88, v70, v96
	v_exp_f32_e32 v97, v88
	v_pk_mul_f32 v[94:95], v[90:91], v[90:91]
	v_mul_f32_e32 v70, v70, v78
	v_mul_f32_e32 v78, v66, v96
	v_add_f32_e32 v90, 1.0, v97
	v_rcp_f32_e32 v90, v90
	v_exp_f32_e32 v78, v78
	v_mul_f32_e32 v66, v66, v74
	v_mul_f32_e32 v74, 0xbfb8aa3b, v91
	v_mul_f32_e32 v90, v94, v90
	v_mul_f32_e32 v70, v70, v90
	ds_write_b32 v134, v70
	v_add_f32_e32 v70, 1.0, v78
	v_rcp_f32_e32 v70, v70
	v_mul_f32_e32 v78, v71, v74
	v_exp_f32_e32 v78, v78
	v_pk_mul_f32 v[88:89], v[92:93], v[92:93]
	v_mul_f32_e32 v70, v94, v70
	v_mul_f32_e32 v66, v66, v70
	ds_write_b32 v134, v66 offset:64
	v_add_f32_e32 v66, 1.0, v78
	v_rcp_f32_e32 v66, v66
	v_mul_f32_e32 v70, v71, v79
	v_mul_f32_e32 v71, v67, v74
	v_exp_f32_e32 v71, v71
	v_mul_f32_e32 v66, v95, v66
	v_mul_f32_e32 v66, v70, v66
	ds_write_b32 v134, v66 offset:144
	v_add_f32_e32 v66, 1.0, v71
	v_rcp_f32_e32 v66, v66
	v_mul_f32_e32 v70, 0xbfb8aa3b, v92
	v_mul_f32_e32 v71, v72, v70
	v_exp_f32_e32 v71, v71
	v_mul_f32_e32 v67, v67, v75
	v_mul_f32_e32 v66, v95, v66
	v_mul_f32_e32 v66, v67, v66
	ds_write_b32 v134, v66 offset:208
	v_add_f32_e32 v66, 1.0, v71
	v_rcp_f32_e32 v66, v66
	v_mul_f32_e32 v70, v68, v70
	v_exp_f32_e32 v70, v70
	v_mul_f32_e32 v67, v72, v80
	v_mul_f32_e32 v66, v88, v66
	v_mul_f32_e32 v66, v67, v66
	ds_write_b32 v134, v66 offset:288
	v_add_f32_e32 v66, 1.0, v70
	v_mul_f32_e32 v67, 0xbfb8aa3b, v93
	v_rcp_f32_e32 v66, v66
	v_mul_f32_e32 v70, v73, v67
	v_exp_f32_e32 v70, v70
	v_mul_f32_e32 v67, v69, v67
	v_exp_f32_e32 v67, v67
	v_mul_f32_e32 v68, v68, v76
	v_mul_f32_e32 v66, v88, v66
	v_mul_f32_e32 v66, v68, v66
	v_add_f32_e32 v68, 1.0, v70
	v_rcp_f32_e32 v68, v68
	v_add_f32_e32 v67, 1.0, v67
	v_rcp_f32_e32 v67, v67
	v_cvt_pk_bf16_f32 v84, v86, v87
	v_add_u32_e32 v86, s46, v135
	ds_write_b32 v134, v66 offset:352
	v_mul_f32_e32 v66, v73, v81
	v_mul_f32_e32 v68, v89, v68
	v_mad_i64_i32 v[86:87], s[16:17], v86, s18, v[116:117]
	v_mul_f32_e32 v66, v66, v68
	v_lshl_add_u64 v[86:87], v[86:87], 0, s[12:13]
	ds_write_b32 v114, v66
	v_mul_f32_e32 v66, v69, v77
	v_mul_f32_e32 v67, v89, v67
	v_mul_f32_e32 v66, v66, v67
	v_lshl_add_u64 v[74:75], v[86:87], 0, s[74:75]
	ds_write_b32 v114, v66 offset:64
	v_lshl_add_u64 v[74:75], v[74:75], 0, v[118:119]
	global_store_dwordx4 v[74:75], v[82:85], off
	ds_read_b128 v[74:77], v142 offset:512
	ds_read_b128 v[66:69], v141
	ds_read_b128 v[70:73], v141 offset:16
	s_waitcnt lgkmcnt(0)
	v_cvt_pk_bf16_f32 v66, v66, v67
	v_cvt_pk_bf16_f32 v67, v68, v69
	v_mul_f32_e32 v80, 0xbfb8aa3b, v74
	v_cvt_pk_bf16_f32 v69, v72, v73
	v_mul_f32_e32 v72, v54, v80
	v_exp_f32_e32 v81, v72
	v_pk_mul_f32 v[78:79], v[74:75], v[74:75]
	v_mul_f32_e32 v54, v54, v62
	v_mul_f32_e32 v62, v50, v80
	v_add_f32_e32 v74, 1.0, v81
	v_rcp_f32_e32 v74, v74
	v_exp_f32_e32 v62, v62
	v_mul_f32_e32 v50, v50, v58
	v_mul_f32_e32 v58, 0xbfb8aa3b, v75
	v_mul_f32_e32 v74, v78, v74
	v_mul_f32_e32 v54, v54, v74
	ds_write_b32 v134, v54
	v_add_f32_e32 v54, 1.0, v62
	v_rcp_f32_e32 v54, v54
	v_mul_f32_e32 v62, v55, v58
	v_exp_f32_e32 v62, v62
	v_pk_mul_f32 v[72:73], v[76:77], v[76:77]
	v_mul_f32_e32 v54, v78, v54
	v_mul_f32_e32 v50, v50, v54
	ds_write_b32 v134, v50 offset:64
	v_add_f32_e32 v50, 1.0, v62
	v_rcp_f32_e32 v50, v50
	v_mul_f32_e32 v54, v55, v63
	v_mul_f32_e32 v55, v51, v58
	v_exp_f32_e32 v55, v55
	v_mul_f32_e32 v50, v79, v50
	v_mul_f32_e32 v50, v54, v50
	ds_write_b32 v134, v50 offset:144
	v_add_f32_e32 v50, 1.0, v55
	v_rcp_f32_e32 v50, v50
	v_mul_f32_e32 v54, 0xbfb8aa3b, v76
	v_mul_f32_e32 v55, v56, v54
	v_exp_f32_e32 v55, v55
	v_mul_f32_e32 v51, v51, v59
	v_mul_f32_e32 v50, v79, v50
	v_mul_f32_e32 v50, v51, v50
	ds_write_b32 v134, v50 offset:208
	v_add_f32_e32 v50, 1.0, v55
	v_rcp_f32_e32 v50, v50
	v_mul_f32_e32 v54, v52, v54
	v_exp_f32_e32 v54, v54
	v_mul_f32_e32 v51, v56, v64
	v_mul_f32_e32 v50, v72, v50
	v_mul_f32_e32 v50, v51, v50
	ds_write_b32 v134, v50 offset:288
	v_add_f32_e32 v50, 1.0, v54
	v_mul_f32_e32 v51, 0xbfb8aa3b, v77
	v_rcp_f32_e32 v50, v50
	v_mul_f32_e32 v54, v57, v51
	v_exp_f32_e32 v54, v54
	v_mul_f32_e32 v51, v53, v51
	v_exp_f32_e32 v51, v51
	v_mul_f32_e32 v52, v52, v60
	v_mul_f32_e32 v50, v72, v50
	v_mul_f32_e32 v50, v52, v50
	v_add_f32_e32 v52, 1.0, v54
	v_rcp_f32_e32 v52, v52
	v_add_f32_e32 v51, 1.0, v51
	v_rcp_f32_e32 v51, v51
	v_cvt_pk_bf16_f32 v68, v70, v71
	v_add_u32_e32 v70, s47, v135
	ds_write_b32 v134, v50 offset:352
	v_mul_f32_e32 v50, v57, v65
	v_mul_f32_e32 v52, v73, v52
	v_mad_i64_i32 v[70:71], s[16:17], v70, s18, v[116:117]
	v_mul_f32_e32 v50, v50, v52
	v_lshl_add_u64 v[70:71], v[70:71], 0, s[12:13]
	ds_write_b32 v114, v50
	v_mul_f32_e32 v50, v53, v61
	v_mul_f32_e32 v51, v73, v51
	v_mul_f32_e32 v50, v50, v51
	v_lshl_add_u64 v[58:59], v[70:71], 0, s[74:75]
	ds_write_b32 v114, v50 offset:64
	v_lshl_add_u64 v[58:59], v[58:59], 0, v[118:119]
	global_store_dwordx4 v[58:59], v[66:69], off
	ds_read_b128 v[58:61], v142 offset:576
	ds_read_b128 v[50:53], v141
	ds_read_b128 v[54:57], v141 offset:16
	s_waitcnt lgkmcnt(0)
	v_cvt_pk_bf16_f32 v50, v50, v51
	v_cvt_pk_bf16_f32 v51, v52, v53
	v_mul_f32_e32 v64, 0xbfb8aa3b, v58
	v_cvt_pk_bf16_f32 v53, v56, v57
	v_mul_f32_e32 v56, v38, v64
	v_exp_f32_e32 v65, v56
	v_pk_mul_f32 v[62:63], v[58:59], v[58:59]
	v_mul_f32_e32 v38, v38, v46
	v_mul_f32_e32 v46, v34, v64
	v_add_f32_e32 v58, 1.0, v65
	v_rcp_f32_e32 v58, v58
	v_exp_f32_e32 v46, v46
	v_mul_f32_e32 v34, v34, v42
	v_mul_f32_e32 v42, 0xbfb8aa3b, v59
	v_mul_f32_e32 v58, v62, v58
	v_mul_f32_e32 v38, v38, v58
	ds_write_b32 v134, v38
	v_add_f32_e32 v38, 1.0, v46
	v_rcp_f32_e32 v38, v38
	v_mul_f32_e32 v46, v39, v42
	v_exp_f32_e32 v46, v46
	v_pk_mul_f32 v[56:57], v[60:61], v[60:61]
	v_mul_f32_e32 v38, v62, v38
	v_mul_f32_e32 v34, v34, v38
	ds_write_b32 v134, v34 offset:64
	v_add_f32_e32 v34, 1.0, v46
	v_rcp_f32_e32 v34, v34
	v_mul_f32_e32 v38, v39, v47
	v_mul_f32_e32 v39, v35, v42
	v_exp_f32_e32 v39, v39
	v_mul_f32_e32 v34, v63, v34
	v_mul_f32_e32 v34, v38, v34
	ds_write_b32 v134, v34 offset:144
	v_add_f32_e32 v34, 1.0, v39
	v_rcp_f32_e32 v34, v34
	v_mul_f32_e32 v38, 0xbfb8aa3b, v60
	v_mul_f32_e32 v39, v40, v38
	v_exp_f32_e32 v39, v39
	v_mul_f32_e32 v35, v35, v43
	v_mul_f32_e32 v34, v63, v34
	v_mul_f32_e32 v34, v35, v34
	ds_write_b32 v134, v34 offset:208
	v_add_f32_e32 v34, 1.0, v39
	v_rcp_f32_e32 v34, v34
	v_mul_f32_e32 v38, v36, v38
	v_exp_f32_e32 v38, v38
	v_mul_f32_e32 v35, v40, v48
	v_mul_f32_e32 v34, v56, v34
	v_mul_f32_e32 v34, v35, v34
	ds_write_b32 v134, v34 offset:288
	v_add_f32_e32 v34, 1.0, v38
	v_mul_f32_e32 v35, 0xbfb8aa3b, v61
	v_rcp_f32_e32 v34, v34
	v_mul_f32_e32 v38, v41, v35
	v_exp_f32_e32 v38, v38
	v_mul_f32_e32 v35, v37, v35
	v_exp_f32_e32 v35, v35
	v_mul_f32_e32 v36, v36, v44
	v_mul_f32_e32 v34, v56, v34
	v_mul_f32_e32 v34, v36, v34
	v_add_f32_e32 v36, 1.0, v38
	v_rcp_f32_e32 v36, v36
	v_add_f32_e32 v35, 1.0, v35
	v_rcp_f32_e32 v35, v35
	v_cvt_pk_bf16_f32 v52, v54, v55
	v_add_u32_e32 v54, 0x80, v115
	ds_write_b32 v134, v34 offset:352
	v_mul_f32_e32 v34, v41, v49
	v_mul_f32_e32 v36, v57, v36
	v_mad_i64_i32 v[54:55], s[16:17], v54, s18, v[116:117]
	v_mul_f32_e32 v34, v34, v36
	v_lshl_add_u64 v[54:55], v[54:55], 0, s[12:13]
	ds_write_b32 v114, v34
	v_mul_f32_e32 v34, v37, v45
	v_mul_f32_e32 v35, v57, v35
	v_mul_f32_e32 v34, v34, v35
	v_lshl_add_u64 v[42:43], v[54:55], 0, s[74:75]
	ds_write_b32 v114, v34 offset:64
	v_lshl_add_u64 v[42:43], v[42:43], 0, v[118:119]
	global_store_dwordx4 v[42:43], v[50:53], off
	ds_read_b128 v[42:45], v142 offset:640
	ds_read_b128 v[34:37], v141
	ds_read_b128 v[38:41], v141 offset:16
	s_waitcnt lgkmcnt(0)
	v_cvt_pk_bf16_f32 v34, v34, v35
	v_cvt_pk_bf16_f32 v35, v36, v37
	v_mul_f32_e32 v48, 0xbfb8aa3b, v42
	v_cvt_pk_bf16_f32 v37, v40, v41
	v_mul_f32_e32 v40, v22, v48
	v_exp_f32_e32 v49, v40
	v_pk_mul_f32 v[46:47], v[42:43], v[42:43]
	v_mul_f32_e32 v22, v22, v30
	v_mul_f32_e32 v30, v18, v48
	v_add_f32_e32 v42, 1.0, v49
	v_rcp_f32_e32 v42, v42
	v_exp_f32_e32 v30, v30
	v_mul_f32_e32 v18, v18, v26
	v_mul_f32_e32 v26, 0xbfb8aa3b, v43
	v_mul_f32_e32 v42, v46, v42
	v_mul_f32_e32 v22, v22, v42
	ds_write_b32 v134, v22
	v_add_f32_e32 v22, 1.0, v30
	v_rcp_f32_e32 v22, v22
	v_mul_f32_e32 v30, v23, v26
	v_exp_f32_e32 v30, v30
	v_pk_mul_f32 v[40:41], v[44:45], v[44:45]
	v_mul_f32_e32 v22, v46, v22
	v_mul_f32_e32 v18, v18, v22
	ds_write_b32 v134, v18 offset:64
	v_add_f32_e32 v18, 1.0, v30
	v_rcp_f32_e32 v18, v18
	v_mul_f32_e32 v22, v23, v31
	v_mul_f32_e32 v23, v19, v26
	v_exp_f32_e32 v23, v23
	v_mul_f32_e32 v18, v47, v18
	v_mul_f32_e32 v18, v22, v18
	ds_write_b32 v134, v18 offset:144
	v_add_f32_e32 v18, 1.0, v23
	v_rcp_f32_e32 v18, v18
	v_mul_f32_e32 v22, 0xbfb8aa3b, v44
	v_mul_f32_e32 v23, v24, v22
	v_exp_f32_e32 v23, v23
	v_mul_f32_e32 v19, v19, v27
	v_mul_f32_e32 v18, v47, v18
	v_mul_f32_e32 v18, v19, v18
	ds_write_b32 v134, v18 offset:208
	v_add_f32_e32 v18, 1.0, v23
	v_rcp_f32_e32 v18, v18
	v_mul_f32_e32 v22, v20, v22
	v_exp_f32_e32 v22, v22
	v_mul_f32_e32 v19, v24, v32
	v_mul_f32_e32 v18, v40, v18
	v_mul_f32_e32 v18, v19, v18
	ds_write_b32 v134, v18 offset:288
	v_add_f32_e32 v18, 1.0, v22
	v_mul_f32_e32 v19, 0xbfb8aa3b, v45
	v_rcp_f32_e32 v18, v18
	v_mul_f32_e32 v22, v25, v19
	v_exp_f32_e32 v22, v22
	v_mul_f32_e32 v19, v21, v19
	v_exp_f32_e32 v19, v19
	v_mul_f32_e32 v20, v20, v28
	v_mul_f32_e32 v18, v40, v18
	v_mul_f32_e32 v18, v20, v18
	v_add_f32_e32 v20, 1.0, v22
	v_rcp_f32_e32 v20, v20
	v_add_f32_e32 v19, 1.0, v19
	v_rcp_f32_e32 v19, v19
	v_cvt_pk_bf16_f32 v36, v38, v39
	v_add_u32_e32 v38, 0x90, v115
	ds_write_b32 v134, v18 offset:352
	v_mul_f32_e32 v18, v25, v33
	v_mul_f32_e32 v20, v41, v20
	v_mad_i64_i32 v[38:39], s[16:17], v38, s18, v[116:117]
	v_mul_f32_e32 v18, v18, v20
	v_lshl_add_u64 v[38:39], v[38:39], 0, s[12:13]
	ds_write_b32 v114, v18
	v_mul_f32_e32 v18, v21, v29
	v_mul_f32_e32 v19, v41, v19
	v_mul_f32_e32 v18, v18, v19
	v_lshl_add_u64 v[26:27], v[38:39], 0, s[74:75]
	ds_write_b32 v114, v18 offset:64
	v_lshl_add_u64 v[26:27], v[26:27], 0, v[118:119]
	global_store_dwordx4 v[26:27], v[34:37], off
	ds_read_b128 v[26:29], v142 offset:704
	ds_read_b128 v[18:21], v141
	ds_read_b128 v[22:25], v141 offset:16
	s_waitcnt lgkmcnt(0)
	v_cvt_pk_bf16_f32 v18, v18, v19
	v_cvt_pk_bf16_f32 v19, v20, v21
	v_mul_f32_e32 v32, 0xbfb8aa3b, v26
	v_cvt_pk_bf16_f32 v21, v24, v25
	v_mul_f32_e32 v24, v6, v32
	v_exp_f32_e32 v33, v24
	v_pk_mul_f32 v[30:31], v[26:27], v[26:27]
	v_mul_f32_e32 v6, v6, v14
	v_mul_f32_e32 v14, v2, v32
	v_add_f32_e32 v26, 1.0, v33
	v_rcp_f32_e32 v26, v26
	v_exp_f32_e32 v14, v14
	v_mul_f32_e32 v2, v2, v10
	v_mul_f32_e32 v10, 0xbfb8aa3b, v27
	v_mul_f32_e32 v26, v30, v26
	v_mul_f32_e32 v6, v6, v26
	ds_write_b32 v134, v6
	v_add_f32_e32 v6, 1.0, v14
	v_rcp_f32_e32 v6, v6
	v_mul_f32_e32 v14, v7, v10
	v_exp_f32_e32 v14, v14
	v_pk_mul_f32 v[24:25], v[28:29], v[28:29]
	v_mul_f32_e32 v6, v30, v6
	v_mul_f32_e32 v2, v2, v6
	ds_write_b32 v134, v2 offset:64
	v_add_f32_e32 v2, 1.0, v14
	v_rcp_f32_e32 v2, v2
	v_mul_f32_e32 v6, v7, v15
	v_mul_f32_e32 v7, v3, v10
	v_exp_f32_e32 v7, v7
	v_mul_f32_e32 v2, v31, v2
	v_mul_f32_e32 v2, v6, v2
	ds_write_b32 v134, v2 offset:144
	v_add_f32_e32 v2, 1.0, v7
	v_rcp_f32_e32 v2, v2
	v_mul_f32_e32 v6, 0xbfb8aa3b, v28
	v_mul_f32_e32 v7, v8, v6
	v_exp_f32_e32 v7, v7
	v_mul_f32_e32 v3, v3, v11
	v_mul_f32_e32 v2, v31, v2
	v_mul_f32_e32 v2, v3, v2
	ds_write_b32 v134, v2 offset:208
	v_add_f32_e32 v2, 1.0, v7
	v_rcp_f32_e32 v2, v2
	v_mul_f32_e32 v6, v4, v6
	v_exp_f32_e32 v6, v6
	v_mul_f32_e32 v3, v8, v16
	v_mul_f32_e32 v2, v24, v2
	v_mul_f32_e32 v2, v3, v2
	ds_write_b32 v134, v2 offset:288
	v_add_f32_e32 v2, 1.0, v6
	v_mul_f32_e32 v3, 0xbfb8aa3b, v29
	v_rcp_f32_e32 v2, v2
	v_mul_f32_e32 v6, v9, v3
	v_exp_f32_e32 v6, v6
	v_mul_f32_e32 v3, v5, v3
	v_exp_f32_e32 v3, v3
	v_mul_f32_e32 v4, v4, v12
	v_mul_f32_e32 v2, v24, v2
	v_mul_f32_e32 v2, v4, v2
	v_add_f32_e32 v4, 1.0, v6
	v_rcp_f32_e32 v4, v4
	v_add_f32_e32 v3, 1.0, v3
	v_rcp_f32_e32 v3, v3
	ds_write_b32 v134, v2 offset:352
	v_mul_f32_e32 v2, v9, v17
	v_mul_f32_e32 v4, v25, v4
	v_mul_f32_e32 v2, v2, v4
	ds_write_b32 v114, v2
	v_mul_f32_e32 v2, v5, v13
	v_mul_f32_e32 v3, v25, v3
	v_mul_f32_e32 v2, v2, v3
	ds_write_b32 v114, v2 offset:64
	ds_read_b128 v[2:5], v141
	ds_read_b128 v[6:9], v141 offset:16
	v_cvt_pk_bf16_f32 v20, v22, v23
	v_add_u32_e32 v22, 0xa0, v115
	s_waitcnt lgkmcnt(0)
	v_cvt_pk_bf16_f32 v2, v2, v3
	v_cvt_pk_bf16_f32 v3, v4, v5
	v_cvt_pk_bf16_f32 v4, v6, v7
	v_add_u32_e32 v6, 0xb0, v115
	v_mad_i64_i32 v[22:23], s[16:17], v22, s18, v[116:117]
	v_mad_i64_i32 v[6:7], s[16:17], v6, s18, v[116:117]
	v_lshl_add_u64 v[22:23], v[22:23], 0, s[12:13]
	v_lshl_add_u64 v[6:7], v[6:7], 0, s[12:13]
	v_lshl_add_u64 v[10:11], v[22:23], 0, s[74:75]
	v_lshl_add_u64 v[6:7], v[6:7], 0, s[74:75]
	v_lshl_add_u64 v[10:11], v[10:11], 0, v[118:119]
	v_lshl_add_u64 v[6:7], v[6:7], 0, v[118:119]
	s_and_b64 vcc, exec, s[14:15]
	global_store_dwordx4 v[10:11], v[18:21], off
	v_cvt_pk_bf16_f32 v5, v8, v9
	global_store_dwordx4 v[6:7], v[2:5], off
	s_waitcnt vmcnt(24)
	v_add_f32_e32 v164, v160, v161
	v_add_f32_e32 v164, v162, v164
	v_add_f32_e32 v164, v163, v164
	v_fmamk_f32 v164, v164, 0x3a800000, v208
	v_mul_f32_e32 v165, 0x4b800000, v164
	v_cmp_gt_f32_e64 s[12:13], s95, v164
	s_nop 1
	v_cndmask_b32_e64 v164, v164, v165, s[12:13]
	v_rsq_f32_e32 v164, v164
	s_nop 0
	v_mul_f32_e32 v165, 0x45800000, v164
	v_cndmask_b32_e64 v252, v164, v165, s[12:13]
	s_barrier
	s_cbranch_vccnz .LBB0_474

.LBB0_471:
	s_add_i32 s49, s49, s73
	s_cmpk_gt_i32 s49, 0xaff
	s_cselect_b64 s[14:15], -1, 0
	s_and_b64 vcc, exec, s[14:15]
	s_cbranch_vccnz .LBB0_458
	s_mul_hi_i32 s13, s49, 0x2e8ba2e9
	s_lshr_b32 s16, s13, 31
	s_ashr_i32 s13, s13, 5
	s_add_i32 s13, s13, s16
	s_lshl_b32 s17, s49, 8
	s_lshl_b32 s16, s13, 11
	s_and_b32 s17, s17, 0x700
	s_or_b32 s16, s16, s17
	s_and_saveexec_b64 s[18:19], s[4:5]
	s_cbranch_execz .LBB0_457
	v_add_u32_e32 v134, s16, v1
	v_ashrrev_i32_e32 v135, 31, v134
	v_lshl_add_u64 v[134:135], v[134:135], 4, s[2:3]
	global_load_dwordx4 v[160:163], v[134:135], off
	s_branch .LBB0_457
